# v18c with never-executed padding so that all 7 hot K-loops start at 0 mod 8 (even in-proj / even out-proj loops moved off 4 mod 8), FFN loops unchanged mod 64
# baseline (speedup 1.0000x reference)
.LBB0_1074:
	s_cmp_lt_u32 s2, 0x1000001
	s_mov_b64 s[28:29], 0
	s_cselect_b64 s[30:31], -1, 0
	s_and_b64 vcc, exec, s[30:31]
	s_cbranch_vccz .LBB0_1068
	s_branch .LBB0_1073
	s_nop 0
.LBB0_1075:
	s_or_b64 exec, exec, s[18:19]
	s_and_b64 s[18:19], s[20:21], exec

; #define PG8_STAGE(bufoff, gbase, voff) do { _Pragma("unroll") for (int _i = 0; _i < 2; ++_i) \
;         __builtin_amdgcn_global_load_lds((const unsigned*)((const char*)(gbase) + (voff)[_i]), (LAS unsigned*)(lds + (bufoff) + ldsw + _i * 8192), 16, 0, 0); } while (0)
; #define PG8_WAIT_V(n) asm volatile("s_waitcnt vmcnt(" #n ")" ::: "memory")
; #define PG8_BAR __builtin_amdgcn_s_barrier()
; template <class Epi, class Sched>
; __device__ __forceinline__ void gemm_phase(LAS unsigned char* lds, const Gemm g, const Sched& S, const Epi& E) {
;     ...
;     const char* cA = (const char*)g.A + (size_t)cur.pm * tstepA; const char* cB = (const char*)g.Bt + (size_t)cur.pn * tstepB;
;     S.a_ready(cur);
;     PG8_STAGE(PG8_SB(0, 0), cB, voffB); PG8_STAGE(PG8_SA(0, 0), cA, voffA); PG8_STAGE(PG8_SB(0, 1), cB + hstepB, voffB); PG8_STAGE(PG8_SA(0, 1), cA + hstepA, voffA);
;     if (wr == 1) PG8_BAR;
;     PG8_WAIT_V(4); PG8_BAR;
;     PG8_STAGE(PG8_SB(1, 0), cB + kstep, voffB); PG8_STAGE(PG8_SA(1, 0), cA + kstep, voffA); PG8_STAGE(PG8_SB(1, 1), cB + hstepB + kstep, voffB);
;     PG8_WAIT_V(6); PG8_BAR;
; __global__ void __launch_bounds__(NTHR, 2) mega(Args args) {
;     ...
;             pg8::Gemm g{RES, (const bf16_t*)(ws + WS_W_UP + layer * SZ_W_UP), M, FF2, D, D};
;             pg8::StaticOrder S; S.init(M, FF2, F.G, F.bid);
;             pg8::EpiFfnGate E{(bf16_t*)(ws + WS_ACT), F.in[I_F_CONVW] + (size_t)layer * 3 * FF, F.in[I_F_CONVB] + (size_t)layer * FF,
;                               (float*)(ws + WS_TAIL), (float*)(ws + WS_HEADG), (float*)(ws + WS_HEADU), F.lds + 131072, RSTD};
;             pg8::gemm_phase(F.lds, g, S, E);
.LBB0_1519:
	v_readlane_b32 s29, v255, 27
	s_mul_i32 s28, s29, 0x10800
	s_mul_hi_u32 s15, s29, 0x10800
	s_waitcnt lgkmcnt(0)
	s_add_u32 s36, s40, s28
	s_addc_u32 s37, s41, s15
	s_mul_i32 s28, s29, 0x5800
	v_readlane_b32 s58, v254, 23
	s_mul_hi_u32 s15, s29, 0x5800
	s_add_u32 s42, s42, s28
	v_mov_b32_e32 v181, v3
	v_readlane_b32 s59, v254, 24
	s_addc_u32 s43, s43, s15
	s_and_b32 s40, s14, 3
	s_add_i32 m0, s20, 0x18000
	v_lshl_add_u64 v[4:5], v[4:5], 0, s[8:9]
	v_lshl_add_u64 v[14:15], s[58:59], 0, v[180:181]
	v_mov_b32_e32 v177, v3
	s_lshl_b32 s28, s5, 6
	s_lshl_b32 s35, s5, 13
	s_lshl_b32 s29, s40, 5
	s_lshl_b32 s38, s40, 12
	s_waitcnt vmcnt(2)
	s_barrier
	global_load_lds_dwordx4 v[4:5], off
	v_lshl_add_u64 v[4:5], v[6:7], 0, s[8:9]
	s_add_i32 m0, s20, 0x1a000
	s_add_i32 s30, s20, 0x8000
	s_add_i32 s31, s20, 0xa000
	v_lshl_add_u64 v[16:17], s[58:59], 0, v[176:177]
	global_load_lds_dwordx4 v[4:5], off
	v_lshl_add_u64 v[4:5], v[14:15], 0, s[8:9]
	s_mov_b32 m0, s30
	s_add_u32 s14, s6, 0x80080
	global_load_lds_dwordx4 v[4:5], off
	v_lshl_add_u64 v[4:5], v[16:17], 0, s[8:9]
	s_mov_b32 m0, s31
	s_addc_u32 s15, s7, 0
	global_load_lds_dwordx4 v[4:5], off
	s_add_i32 m0, s20, 0x1c000
	v_lshl_add_u64 v[4:5], s[14:15], 0, v[178:179]
	global_load_lds_dwordx4 v[4:5], off
	v_lshl_add_u64 v[4:5], s[14:15], 0, v[174:175]
	s_add_i32 m0, s20, 0x1e000
	s_movk_i32 s14, 0x3c0
	global_load_lds_dwordx4 v[4:5], off
	v_and_b32_e32 v4, 48, v1
	v_lshlrev_b32_e32 v5, 6, v1
	v_lshlrev_b32_e32 v1, 2, v1
	v_and_or_b32 v4, v5, s14, v4
	v_and_b32_e32 v1, 32, v1
	s_and_b32 s14, s4, 0xffffff00
	v_bitop3_b32 v5, v4, s35, v1 bitop3:0xde
	s_add_i32 s35, s14, 0
	s_lshl_b32 s14, s5, 5
	s_lshl_b32 s15, s40, 3
	v_bitop3_b32 v1, v4, s38, v1 bitop3:0xde
	s_or_b32 s38, s15, s14
	s_add_i32 s35, s35, 0x21000
	s_add_i32 s39, s38, 64
	s_cmpk_gt_u32 s4, 0xff
	s_cselect_b64 s[44:45], -1, 0
	s_lshl_b32 s40, s40, 8
	s_cmp_lg_u32 s5, 1
	s_cselect_b64 s[14:15], -1, 0
	v_cndmask_b32_e64 v4, 0, 1, s[14:15]
	s_and_b64 s[14:15], s[14:15], exec
	s_cselect_b32 s14, 0, 2
	v_readfirstlane_b32 s15, v4
	s_cselect_b32 s5, 0x400, 0
	s_or_b32 s14, s14, s15
	s_lshl_b32 s14, s14, 10
	v_lshlrev_b32_e32 v4, 15, v11
	s_cmpk_lt_u32 s4, 0x100
	v_and_b32_e32 v4, 0xffff0000, v4
	s_cselect_b64 s[46:47], -1, 0
	s_add_u32 s48, s36, 0x5800
	v_lshl_add_u32 v4, v10, 12, v4
	v_and_b32_e32 v6, 1, v11
	s_addc_u32 s49, s37, 0
	v_lshl_or_b32 v4, v6, 6, v4
	s_add_u32 s50, s36, 0xb000
	v_lshl_add_u32 v182, v12, 1, v4
	v_lshlrev_b32_e32 v4, 15, v2
	s_addc_u32 s51, s37, 0
	s_add_i32 s62, 0, 0x20000
	v_and_b32_e32 v4, 0xffff0000, v4
	s_waitcnt vmcnt(6)
	s_add_i32 s63, s62, s5
	v_lshl_add_u32 v4, v8, 12, v4
	v_and_b32_e32 v2, 1, v2
	v_readlane_b32 s4, v254, 21
	s_add_i32 s64, s62, s14
	v_lshl_or_b32 v2, v2, 6, v4
	v_readlane_b32 s5, v254, 22
	s_mov_b32 s66, 0
	s_add_i32 s63, s63, s40
	s_add_i32 s64, s64, s40
	v_mov_b32_e32 v183, v3
	v_lshl_add_u32 v184, v9, 1, v2
	v_mov_b32_e32 v185, v3
	v_add_u32_e32 v207, 0, v5
	v_readlane_b32 s53, v254, 18
	s_mov_b32 s52, s4
	s_mov_b64 s[4:5], s[58:59]
	s_barrier
	s_branch .LBB0_1521
	s_nop 0
	s_nop 0
	s_nop 0
	s_nop 0
	s_nop 0
	s_nop 0
	s_nop 0
	s_nop 0
	s_nop 0
	s_nop 0
	s_nop 0
	s_nop 0
	s_nop 0
	s_nop 0
	s_nop 0
